# phase 2 only: static s_setprio 1 for waves 4..7, reset at phase 3
# baseline (speedup 1.0000x reference)
.LBB0_668:
	v_readfirstlane_b32 s101, v162
	s_nop 3
	s_lshr_b32 s101, s101, 6
	s_cmp_ge_u32 s101, 4
	s_cbranch_scc0 .Lp2prio_done
	s_setprio 1

.LBB0_974:
	s_setprio 0
	s_cmpk_lt_i32 s92, 0x100
	v_readfirstlane_b32 s23, v162
	s_movk_i32 s0, 0x400
	s_cselect_b64 s[2:3], -1, 0
	s_cmpk_gt_i32 s92, 0xff
	s_cbranch_scc1 .LBB0_980
	s_ashr_i32 s1, s92, 31
	s_lshr_b32 s1, s1, 29
	s_add_i32 s1, s92, s1
	s_and_b32 s4, s1, -8
	s_sub_i32 s6, s92, s4
	s_cmp_gt_i32 s6, -1
	s_cbranch_scc0 .LBB0_977
	s_lshl_b32 s7, s6, 5
	s_cbranch_execz .LBB0_978
	s_branch .LBB0_979
